# attention passes no longer drain vmcnt(0) at pass start (in-order vmcnt already covers the previous pass's stores); otherwise v19
# baseline (speedup 1.0000x reference)
; DI int tid_fresh() { int t = threadIdx.x; asm volatile("" : "+v"(t)); return t; }
; template <int DK>
; DI void attn_pass(const AttnSrc& s, const int q0, const float sc, LAS unsigned char* lds, f32x16 (&O)[4]) {
;     ...
;   const int tid = tid_fresh(), lane = tid & 63, wid = __builtin_amdgcn_readfirstlane(tid >> 6), r = lane & 31, h = lane >> 5;
;   const int qw0 = q0 + wid * 32;
;   asm volatile("s_waitcnt vmcnt(0)" ::: "memory");
; #pragma unroll
;   for (int i = 0; i < 4; ++i)
; #pragma unroll
;     for (int j = 0; j < 16; ++j) O[i][j] = 0.f;
;   float mrun = (DK == 64) ? 0.f : -INFINITY, lrun = 0.f;
;   const int NT = (q0 + 256) / 64;
;   const bf16_t* kp[KP]; int kstr[KP]; const bf16_t* vp[2];
; #pragma unroll
;   for (int i = 0; i < KP; ++i) {
;     const int o = (wid + 8 * i) * 1024 + lane * 16, row = o / ROWB, pc = (o % ROWB) >> 4;
;     const int lc = (DK == 64) ? (pc ^ (row & 7)) : ((pc & ~7) | ((pc & 7) ^ ((row >> 1) & 7)));
;     const int e = lc * 8;
;     if (e < s.nk0) { kp[i] = s.k0 + (size_t)row * s.ldk0 + e; kstr[i] = 64 * s.ldk0; } else { kp[i] = s.k1 + (size_t)row * s.ldk1 + (e - s.nk0); kstr[i] = 64 * s.ldk1; }
;   }
; #pragma unroll
;   for (int i = 0; i < 2; ++i) {
;     const int o = (wid + 8 * i) * 1024 + lane * 16, row = o >> 8, pc = (o >> 4) & 15;
;     const int lc = (((pc >> 2) ^ (row & 3)) << 2) | (pc & 3);
;     vp[i] = s.v + (size_t)row * s.ldv + lc * 8;
;   }
;   const int vstr = 64 * s.ldv;
;   const unsigned lds0 = (unsigned)reinterpret_cast<__UINTPTR_TYPE__>(lds);
;   auto issue = [&](int t, int buf) {
; #pragma unroll
;     for (int i = 0; i < KP; ++i) glds16(kp[i] + (size_t)t * kstr[i], (unsigned)__builtin_amdgcn_readfirstlane(lds0 + buf * STG + (wid + 8 * i) * 1024));
; #pragma unroll
;     for (int i = 0; i < 2; ++i) glds16(vp[i] + (size_t)t * vstr, (unsigned)__builtin_amdgcn_readfirstlane(lds0 + buf * STG + KSZ + (wid + 8 * i) * 1024));
;   };
; #pragma unroll
;   for (int i = 0; i < DPF; ++i) issue(i, i);
;   bf16x8 qf[NS];
; #pragma unroll
;   for (int i = 0; i < NS; ++i) qf[i] = *(const bf16x8*)(s.q + (size_t)(qw0 + r) * s.ldq + 16 * i + 8 * h);
; #pragma unroll
;   for (int i = 0; i < NS; ++i) asm volatile("" : "+v"(qf[i]));
.LBB0_99:
	s_xor_b64 s[10:11], s[12:13], -1
	s_lshl_b64 s[14:15], s[14:15], 1
	v_mov_b32_e32 v24, v163
	s_add_u32 s14, s22, s14
	s_addc_u32 s15, s23, s15
	v_readfirstlane_b32 s18, v24
	s_ashr_i32 s18, s18, 6
	s_lshl_b32 s45, s18, 5
	v_and_b32_e32 v0, 63, v24
	s_lshl_b32 s18, s18, 10
	v_lshl_or_b32 v8, v0, 4, s18
	v_ashrrev_i32_e32 v0, 31, v8
	v_lshrrev_b32_e32 v0, 25, v0
	v_add_u32_e32 v0, v8, v0
	v_ashrrev_i32_e32 v3, 7, v0
	v_and_b32_e32 v0, 0xffffff80, v0
	v_sub_u32_e32 v0, v8, v0
	v_ashrrev_i32_e32 v0, 4, v0
	v_lshrrev_b32_e32 v4, 1, v3
	v_bitop3_b32 v9, v0, v4, 7 bitop3:0x78
	v_lshlrev_b32_e32 v2, 3, v9
	v_mov_b64_e32 v[4:5], s[14:15]
	v_mad_i64_i32 v[6:7], s[14:15], v3, s59, v[4:5]
	v_ashrrev_i32_e32 v3, 31, v2
	v_ashrrev_i32_e32 v0, 8, v8
	v_lshl_add_u64 v[2:3], v[2:3], 1, v[6:7]
	v_lshlrev_b32_e32 v6, 2, v0
	v_and_b32_e32 v10, 3, v24
	v_xor_b32_e32 v6, v6, v24
	v_and_or_b32 v11, v6, 12, v10
	v_mul_hi_i32_i24_e32 v7, 0x1800, v0
	v_mul_i32_i24_e32 v6, 0x1800, v0
	v_lshl_add_u64 v[6:7], s[4:5], 0, v[6:7]
	v_lshlrev_b32_e32 v0, 4, v11
	v_lshl_add_u64 v[18:19], v[6:7], 0, v[0:1]
	v_add_u32_e32 v0, 0x2000, v8
	v_ashrrev_i32_e32 v0, 8, v0
	v_lshlrev_b32_e32 v6, 2, v0
	v_xor_b32_e32 v6, v6, v24
	v_and_or_b32 v8, v6, 12, v10
	v_mul_hi_i32_i24_e32 v7, 0x1800, v0
	v_mul_i32_i24_e32 v6, 0x1800, v0
	v_lshl_add_u64 v[6:7], s[4:5], 0, v[6:7]
	v_lshlrev_b32_e32 v0, 4, v8
	v_cmp_gt_i32_e32 vcc, 8, v9
	v_lshl_add_u64 v[20:21], v[6:7], 0, v[0:1]
	s_mov_b64 s[14:15], 0x800
	v_cndmask_b32_e64 v7, -1, 0, vcc
	v_cndmask_b32_e64 v6, v200, 0, vcc
	v_lshl_add_u64 v[22:23], v[2:3], 0, v[6:7]
	v_lshl_add_u64 v[2:3], v[22:23], 0, s[14:15]
	s_add_i32 s46, s18, 0
	s_mov_b32 s14, m0
	s_mov_b32 m0, s46
	s_nop 0
	global_load_lds_dwordx4 v[2:3], off
	s_mov_b32 m0, s14
	s_add_i32 s47, s46, 0x2000
	s_mov_b32 s14, m0
	s_mov_b32 m0, s47
	s_nop 0
	global_load_lds_dwordx4 v[18:19], off
	s_mov_b32 m0, s14
	s_add_i32 s52, s46, 0x4000
	s_mov_b32 s14, m0
	s_mov_b32 m0, s52
	s_nop 0
	global_load_lds_dwordx4 v[20:21], off
	s_mov_b32 m0, s14
	s_mov_b64 s[14:15], 0x60800
	v_lshl_add_u64 v[2:3], v[22:23], 0, s[14:15]
	s_add_i32 s14, s46, 0x6000
	s_mov_b32 s15, m0
	s_mov_b32 m0, s14
	s_nop 0
	global_load_lds_dwordx4 v[2:3], off
	s_mov_b32 m0, s15
	v_lshl_add_u64 v[2:3], v[18:19], 0, s[26:27]
	s_add_i32 s14, s46, 0x8000
	s_mov_b32 s15, m0
	s_mov_b32 m0, s14
	s_nop 0
	global_load_lds_dwordx4 v[2:3], off
	s_mov_b32 m0, s15
	v_lshl_add_u64 v[2:3], v[20:21], 0, s[26:27]
	s_add_i32 s14, s46, 0xa000
	s_mov_b32 s15, m0
	s_mov_b32 m0, s14
	s_nop 0
	global_load_lds_dwordx4 v[2:3], off
	s_mov_b32 m0, s15
	s_mov_b64 s[14:15], 0xc0800
	v_lshl_add_u64 v[2:3], v[22:23], 0, s[14:15]
	s_add_i32 s14, s46, 0xc000
	v_and_b32_e32 v25, 31, v24
	s_add_i32 s45, s45, s40
	s_mov_b32 s15, m0
	s_mov_b32 m0, s14
	s_nop 0
	global_load_lds_dwordx4 v[2:3], off
	s_mov_b32 m0, s15
	v_lshl_add_u64 v[2:3], v[18:19], 0, s[28:29]
	s_add_i32 s14, s46, 0xe000
	v_bfe_u32 v26, v24, 5, 1
	s_mov_b32 s15, m0
	s_mov_b32 m0, s14
	s_nop 0
	global_load_lds_dwordx4 v[2:3], off
	s_mov_b32 m0, s15
	v_lshl_add_u64 v[2:3], v[20:21], 0, s[28:29]
	s_add_i32 s14, s46, 0x10000
	v_or_b32_e32 v212, s45, v25
	s_mov_b32 s15, m0
	s_mov_b32 m0, s14
	s_nop 0
	global_load_lds_dwordx4 v[2:3], off
	s_mov_b32 m0, s15
	v_lshlrev_b32_e32 v0, 4, v26
	v_mad_i64_i32 v[2:3], s[14:15], v212, s59, v[4:5]
	v_lshl_add_u64 v[14:15], v[2:3], 0, v[0:1]
	global_load_dwordx4 v[2:5], v[14:15], off
	global_load_dwordx4 v[6:9], v[14:15], off offset:32
	global_load_dwordx4 v[10:13], v[14:15], off offset:64
	s_nop 0
	global_load_dwordx4 v[14:17], v[14:15], off offset:96
	s_mov_b64 s[14:15], 0x120800
	v_lshlrev_b32_e32 v213, 7, v25
	v_lshlrev_b32_e32 v214, 10, v26
	v_lshlrev_b32_e32 v223, 2, v26
	v_lshl_add_u64 v[166:167], v[20:21], 0, s[30:31]
	v_lshl_add_u64 v[168:169], v[18:19], 0, s[30:31]
	v_lshl_add_u64 v[170:171], v[22:23], 0, s[14:15]
	s_mov_b32 s53, 63
	s_mov_b32 s54, 3
	s_mov_b32 s55, 0
	s_or_b32 s56, s45, 31
	v_mov_b32_e32 v227, 0
	s_mov_b32 s57, s44
	s_mov_b64 s[14:15], 0
	s_mov_b32 s58, 3
	s_waitcnt vmcnt(3)
	s_nop 0
	v_lshlrev_b32_e32 v0, 16, v2
	v_and_b32_e32 v2, 0xffff0000, v2
	v_mul_f32_e32 v2, 0x3e38aa3b, v2
	s_waitcnt vmcnt(2)
	s_waitcnt vmcnt(1)
	s_waitcnt vmcnt(0)
; DI unsigned cvt_pk_bf16(float lo, float hi) { unsigned r; asm volatile("v_cvt_pk_bf16_f32 %0, %1, %2" : "=v"(r) : "v"(lo), "v"(hi)); return r; }
; DI float bf_lo(unsigned w) { return __uint_as_float(w << 16); }
; DI float bf_hi(unsigned w) { return __uint_as_float(w & 0xffff0000u); }
; template <int DK>
; DI void attn_pass(const AttnSrc& s, const int q0, const float sc, LAS unsigned char* lds, f32x16 (&O)[4]) {
;     ...
;   constexpr bool REL = (DK == 64);
;   if (REL) {
; #pragma unroll
;   for (int i = 0; i < NS; ++i) {
;     const u32x4 w = __builtin_bit_cast(u32x4, qf[i]); u32x4 o;
;     o.x = cvt_pk_bf16(bf_lo(w.x) * sc, bf_hi(w.x) * sc); o.y = cvt_pk_bf16(bf_lo(w.y) * sc, bf_hi(w.y) * sc);
;     o.z = cvt_pk_bf16(bf_lo(w.z) * sc, bf_hi(w.z) * sc); o.w = cvt_pk_bf16(bf_lo(w.w) * sc, bf_hi(w.w) * sc);
;     qf[i] = __builtin_bit_cast(bf16x8, o);
;   }
;   }
;   f32x16 negm;
; #pragma unroll
;   for (int j = 0; j < 16; ++j) negm[j] = 0.f;
;   if (REL) asm volatile("" : "+v"(negm));
;   const int kx = (DK == 64) ? (r & 7) : ((r >> 1) & 7);
;   const int krow = r * ROWB;
;   const int i15 = lane & 15;
;   const int vrow = (4 * h + (i15 >> 2)) * 256 + ((lane >> 4) & 1) * 32 + (lane & 3) * 8;
;   const int vx = (i15 >> 2) & 3;
;   int buf = 0, pbuf = DPF;
	v_lshlrev_b32_e32 v29, 16, v5
	v_mul_f32_e32 v0, 0x3e38aa3b, v0
	v_cvt_pk_bf16_f32 v128, v0, v2
	v_and_b32_e32 v2, 0xffff0000, v5
	v_lshlrev_b32_e32 v27, 16, v3
	v_and_b32_e32 v3, 0xffff0000, v3
	v_lshlrev_b32_e32 v28, 16, v4
	v_and_b32_e32 v4, 0xffff0000, v4
	v_mul_f32_e32 v0, 0x3e38aa3b, v29
	v_mul_f32_e32 v2, 0x3e38aa3b, v2
	v_mul_f32_e32 v27, 0x3e38aa3b, v27
	v_mul_f32_e32 v3, 0x3e38aa3b, v3
	v_mul_f32_e32 v28, 0x3e38aa3b, v28
	v_mul_f32_e32 v4, 0x3e38aa3b, v4
	v_cvt_pk_bf16_f32 v129, v27, v3
	v_cvt_pk_bf16_f32 v130, v28, v4
	v_cvt_pk_bf16_f32 v131, v0, v2
	v_lshlrev_b32_e32 v0, 16, v6
	v_and_b32_e32 v2, 0xffff0000, v6
	v_mul_f32_e32 v0, 0x3e38aa3b, v0
	v_mul_f32_e32 v2, 0x3e38aa3b, v2
	v_cvt_pk_bf16_f32 v132, v0, v2
	v_lshlrev_b32_e32 v0, 16, v7
	v_and_b32_e32 v2, 0xffff0000, v7
	v_mul_f32_e32 v0, 0x3e38aa3b, v0
	v_mul_f32_e32 v2, 0x3e38aa3b, v2
	v_cvt_pk_bf16_f32 v133, v0, v2
	v_lshlrev_b32_e32 v0, 16, v8
	v_and_b32_e32 v2, 0xffff0000, v8
	v_mul_f32_e32 v0, 0x3e38aa3b, v0
	v_mul_f32_e32 v2, 0x3e38aa3b, v2
	v_cvt_pk_bf16_f32 v134, v0, v2
	v_lshlrev_b32_e32 v0, 16, v9
	v_and_b32_e32 v2, 0xffff0000, v9
	v_mul_f32_e32 v0, 0x3e38aa3b, v0
	v_mul_f32_e32 v2, 0x3e38aa3b, v2
	v_cvt_pk_bf16_f32 v135, v0, v2
	v_lshlrev_b32_e32 v0, 16, v10
	v_and_b32_e32 v2, 0xffff0000, v10
	v_mul_f32_e32 v0, 0x3e38aa3b, v0
	v_mul_f32_e32 v2, 0x3e38aa3b, v2
	v_cvt_pk_bf16_f32 v136, v0, v2
	v_lshlrev_b32_e32 v0, 16, v11
	v_and_b32_e32 v2, 0xffff0000, v11
	v_mul_f32_e32 v0, 0x3e38aa3b, v0
	v_mul_f32_e32 v2, 0x3e38aa3b, v2
	v_cvt_pk_bf16_f32 v137, v0, v2
	v_lshlrev_b32_e32 v0, 16, v12
	v_and_b32_e32 v2, 0xffff0000, v12
	v_mul_f32_e32 v0, 0x3e38aa3b, v0
	v_mul_f32_e32 v2, 0x3e38aa3b, v2
	v_cvt_pk_bf16_f32 v138, v0, v2
	v_lshlrev_b32_e32 v0, 16, v13
	v_and_b32_e32 v2, 0xffff0000, v13
	v_mul_f32_e32 v0, 0x3e38aa3b, v0
	v_mul_f32_e32 v2, 0x3e38aa3b, v2
	v_cvt_pk_bf16_f32 v139, v0, v2
	v_lshlrev_b32_e32 v0, 16, v14
	v_and_b32_e32 v2, 0xffff0000, v14
	v_mul_f32_e32 v0, 0x3e38aa3b, v0
	v_mul_f32_e32 v2, 0x3e38aa3b, v2
	v_cvt_pk_bf16_f32 v140, v0, v2
	v_lshlrev_b32_e32 v0, 16, v15
	v_and_b32_e32 v2, 0xffff0000, v15
	v_mul_f32_e32 v0, 0x3e38aa3b, v0
	v_mul_f32_e32 v2, 0x3e38aa3b, v2
	v_cvt_pk_bf16_f32 v141, v0, v2
	v_lshlrev_b32_e32 v0, 16, v16
	v_and_b32_e32 v2, 0xffff0000, v16
	v_mul_f32_e32 v0, 0x3e38aa3b, v0
	v_mul_f32_e32 v2, 0x3e38aa3b, v2
	v_cvt_pk_bf16_f32 v142, v0, v2
	v_lshlrev_b32_e32 v0, 16, v17
	v_and_b32_e32 v2, 0xffff0000, v17
	v_lshlrev_b32_e32 v17, 1, v24
	v_and_b32_e32 v216, 32, v17
	v_lshlrev_b32_e32 v17, 3, v24
	v_bfe_u32 v16, v24, 2, 2
	v_and_b32_e32 v217, 24, v17
	v_bfe_u32 v17, v24, 1, 3
	v_bitop3_b32 v24, v26, v17, 7 bitop3:0x78
	v_lshlrev_b32_e32 v218, 4, v24
	v_bitop3_b32 v24, v26, v17, 2 bitop3:0x36
	v_mul_f32_e32 v0, 0x3e38aa3b, v0
	v_mul_f32_e32 v2, 0x3e38aa3b, v2
	v_mov_b32_e32 v14, v1
	v_mov_b32_e32 v15, v1
	v_lshlrev_b32_e32 v219, 4, v24
	v_bitop3_b32 v24, v26, v17, 4 bitop3:0x36
	v_bitop3_b32 v17, v26, v17, 6 bitop3:0x36
	v_cvt_pk_bf16_f32 v143, v0, v2
	v_mov_b32_e32 v0, v1
	v_mov_b32_e32 v2, v1
	v_mov_b32_e32 v3, v1
	v_mov_b32_e32 v4, v1
	v_mov_b32_e32 v5, v1
	v_mov_b32_e32 v6, v1
	v_mov_b32_e32 v7, v1
	v_mov_b32_e32 v8, v1
	v_mov_b32_e32 v9, v1
	v_mov_b32_e32 v10, v1
	v_mov_b32_e32 v11, v1
	v_mov_b32_e32 v12, v1
	v_mov_b32_e32 v13, v1
	v_mov_b64_e32 v[94:95], v[14:15]
	v_lshlrev_b32_e32 v215, 8, v16
	v_lshlrev_b32_e32 v220, 4, v24
	v_lshlrev_b32_e32 v221, 4, v17
	v_lshlrev_b32_e32 v222, 6, v16
	v_mov_b64_e32 v[30:31], v[14:15]
	v_mov_b64_e32 v[46:47], v[14:15]
	v_mov_b64_e32 v[62:63], v[14:15]
	v_mov_b64_e32 v[78:79], v[14:15]
	v_mov_b64_e32 v[92:93], v[12:13]
	v_mov_b64_e32 v[90:91], v[10:11]
	v_mov_b64_e32 v[88:89], v[8:9]
	v_mov_b64_e32 v[86:87], v[6:7]
	v_mov_b64_e32 v[84:85], v[4:5]
	v_mov_b64_e32 v[82:83], v[2:3]
	v_mov_b64_e32 v[80:81], v[0:1]
	v_xor_b32_e32 v224, 64, v222
	v_xor_b32_e32 v225, 0x80, v222
	v_xor_b32_e32 v226, 0xc0, v222
	v_mov_b64_e32 v[28:29], v[12:13]
	v_mov_b64_e32 v[26:27], v[10:11]
	v_mov_b64_e32 v[24:25], v[8:9]
	v_mov_b64_e32 v[22:23], v[6:7]
	v_mov_b64_e32 v[20:21], v[4:5]
	v_mov_b64_e32 v[18:19], v[2:3]
	v_mov_b64_e32 v[16:17], v[0:1]
	v_mov_b64_e32 v[44:45], v[12:13]
	v_mov_b64_e32 v[42:43], v[10:11]
	v_mov_b64_e32 v[40:41], v[8:9]
	v_mov_b64_e32 v[38:39], v[6:7]
	v_mov_b64_e32 v[36:37], v[4:5]
	v_mov_b64_e32 v[34:35], v[2:3]
	v_mov_b64_e32 v[32:33], v[0:1]
	v_mov_b64_e32 v[60:61], v[12:13]
	v_mov_b64_e32 v[58:59], v[10:11]
	v_mov_b64_e32 v[56:57], v[8:9]
	v_mov_b64_e32 v[54:55], v[6:7]
	v_mov_b64_e32 v[52:53], v[4:5]
	v_mov_b64_e32 v[50:51], v[2:3]
	v_mov_b64_e32 v[48:49], v[0:1]
	v_mov_b64_e32 v[76:77], v[12:13]
	v_mov_b64_e32 v[74:75], v[10:11]
	v_mov_b64_e32 v[72:73], v[8:9]
	v_mov_b64_e32 v[70:71], v[6:7]
	v_mov_b64_e32 v[68:69], v[4:5]
	v_mov_b64_e32 v[66:67], v[2:3]
	v_mov_b64_e32 v[64:65], v[0:1]
	v_mov_b32_e32 v14, 0
	s_branch .LBB0_102

; template <int DK>
; DI void attn_pass(const AttnSrc& s, const int q0, const float sc, LAS unsigned char* lds, f32x16 (&O)[4]) {
;     ...
;   const int NT = (q0 + 256) / 64;
;   const bf16_t* kp[KP]; int kstr[KP]; const bf16_t* vp[2];
; #pragma unroll
;   for (int i = 0; i < KP; ++i) {
;     const int o = (wid + 8 * i) * 1024 + lane * 16, row = o / ROWB, pc = (o % ROWB) >> 4;
;     const int lc = (DK == 64) ? (pc ^ (row & 7)) : ((pc & ~7) | ((pc & 7) ^ ((row >> 1) & 7)));
;     const int e = lc * 8;
;     if (e < s.nk0) { kp[i] = s.k0 + (size_t)row * s.ldk0 + e; kstr[i] = 64 * s.ldk0; } else { kp[i] = s.k1 + (size_t)row * s.ldk1 + (e - s.nk0); kstr[i] = 64 * s.ldk1; }
;   }
; #pragma unroll
;   for (int i = 0; i < 2; ++i) {
;     const int o = (wid + 8 * i) * 1024 + lane * 16, row = o >> 8, pc = (o >> 4) & 15;
;     const int lc = (((pc >> 2) ^ (row & 3)) << 2) | (pc & 3);
;     vp[i] = s.v + (size_t)row * s.ldv + lc * 8;
;   }
;   const int vstr = 64 * s.ldv;
;   const unsigned lds0 = (unsigned)reinterpret_cast<__UINTPTR_TYPE__>(lds);
;   auto issue = [&](int t, int buf) {
; #pragma unroll
;     for (int i = 0; i < KP; ++i) glds16(kp[i] + (size_t)t * kstr[i], (unsigned)__builtin_amdgcn_readfirstlane(lds0 + buf * STG + (wid + 8 * i) * 1024));
; #pragma unroll
;     for (int i = 0; i < 2; ++i) glds16(vp[i] + (size_t)t * vstr, (unsigned)__builtin_amdgcn_readfirstlane(lds0 + buf * STG + KSZ + (wid + 8 * i) * 1024));
;   };
; #pragma unroll
.LBB0_123:
	v_mov_b32_e32 v16, v163
	s_nop 0
	v_readfirstlane_b32 s12, v16
	s_ashr_i32 s40, s12, 6
	v_and_b32_e32 v18, 63, v16
	s_lshl_b32 s41, s40, 10
	v_lshl_or_b32 v17, v18, 4, s41
	v_mul_hi_i32 v0, v17, s60
	v_lshrrev_b32_e32 v2, 31, v0
	v_ashrrev_i32_e32 v0, 6, v0
	v_add_u32_e32 v8, v0, v2
	v_mul_i32_i24_e32 v0, 0x180, v8
	v_sub_u32_e32 v0, v17, v0
	v_ashrrev_i32_e32 v0, 4, v0
	v_lshrrev_b32_e32 v2, 1, v8
	v_bitop3_b32 v0, v2, v0, 7 bitop3:0x6c
	v_lshlrev_b32_e32 v6, 3, v0
	v_cmp_lt_i32_e32 vcc, 15, v0
	v_ashrrev_i32_e32 v9, 31, v8
	s_and_saveexec_b64 s[12:13], vcc
	s_xor_b64 s[12:13], exec, s[12:13]
	v_mul_hi_i32_i24_e32 v3, 0xc00, v8
	v_mul_i32_i24_e32 v2, 0xc00, v8
	v_lshl_add_u64 v[2:3], s[8:9], 0, v[2:3]
	v_mov_b32_e32 v7, v1
	v_lshl_add_u64 v[2:3], v[6:7], 1, v[2:3]
	v_lshl_add_u64 v[2:3], v[2:3], 0, s[34:35]
	s_or_saveexec_b64 s[12:13], s[12:13]
	v_mov_b64_e32 v[4:5], 0x18000
	s_xor_b64 exec, exec, s[12:13]
	v_lshlrev_b64 v[2:3], 12, v[8:9]
	v_lshl_add_u64 v[2:3], s[6:7], 0, v[2:3]
	v_ashrrev_i32_e32 v7, 31, v6
	v_lshl_add_u64 v[2:3], v[6:7], 1, v[2:3]
	v_mov_b64_e32 v[4:5], 0x20000
	s_or_b64 exec, exec, s[12:13]
	v_add_u32_e32 v5, 0x2000, v17
	v_mul_hi_i32 v0, v5, s60
	v_lshrrev_b32_e32 v6, 31, v0
	v_ashrrev_i32_e32 v0, 6, v0
	v_add_u32_e32 v10, v0, v6
	v_mul_i32_i24_e32 v0, 0x180, v10
	v_sub_u32_e32 v0, v5, v0
	v_ashrrev_i32_e32 v0, 4, v0
	v_lshrrev_b32_e32 v6, 1, v10
	v_bitop3_b32 v6, v6, v0, 7 bitop3:0x6c
	v_lshlrev_b32_e32 v0, 3, v6
	v_cmp_lt_i32_e32 vcc, 15, v6
	v_ashrrev_i32_e32 v11, 31, v10
	s_and_saveexec_b64 s[12:13], vcc
	s_xor_b64 s[12:13], exec, s[12:13]
	v_mul_hi_i32_i24_e32 v7, 0xc00, v10
	v_mul_i32_i24_e32 v6, 0xc00, v10
	v_lshl_add_u64 v[6:7], s[8:9], 0, v[6:7]
	v_lshl_add_u64 v[6:7], v[0:1], 1, v[6:7]
	v_lshl_add_u64 v[6:7], v[6:7], 0, s[34:35]
	s_or_saveexec_b64 s[12:13], s[12:13]
	v_mov_b64_e32 v[8:9], 0x18000
	s_xor_b64 exec, exec, s[12:13]
	v_lshlrev_b64 v[6:7], 12, v[10:11]
	v_lshl_add_u64 v[6:7], s[6:7], 0, v[6:7]
	v_ashrrev_i32_e32 v9, 31, v0
	v_mov_b32_e32 v8, v0
	v_lshl_add_u64 v[6:7], v[8:9], 1, v[6:7]
	v_mov_b64_e32 v[8:9], 0x20000
	s_or_b64 exec, exec, s[12:13]
	v_add_u32_e32 v0, 0x4000, v17
	v_mul_hi_i32 v9, v0, s60
	v_lshrrev_b32_e32 v10, 31, v9
	v_ashrrev_i32_e32 v9, 6, v9
	v_add_u32_e32 v14, v9, v10
	v_mul_i32_i24_e32 v9, 0x180, v14
	v_sub_u32_e32 v0, v0, v9
	v_ashrrev_i32_e32 v0, 4, v0
	v_lshrrev_b32_e32 v9, 1, v14
	v_bitop3_b32 v9, v9, v0, 7 bitop3:0x6c
	v_lshlrev_b32_e32 v0, 3, v9
	v_cmp_lt_i32_e32 vcc, 15, v9
	v_ashrrev_i32_e32 v15, 31, v14
	s_and_saveexec_b64 s[12:13], vcc
	s_xor_b64 s[12:13], exec, s[12:13]
	v_mul_hi_i32_i24_e32 v11, 0xc00, v14
	v_mul_i32_i24_e32 v10, 0xc00, v14
	v_lshl_add_u64 v[10:11], s[8:9], 0, v[10:11]
	v_lshl_add_u64 v[10:11], v[0:1], 1, v[10:11]
	v_lshl_add_u64 v[10:11], v[10:11], 0, s[34:35]
	s_or_saveexec_b64 s[12:13], s[12:13]
	v_mov_b64_e32 v[12:13], 0x18000
	s_xor_b64 exec, exec, s[12:13]
	v_lshlrev_b64 v[10:11], 12, v[14:15]
	v_lshl_add_u64 v[10:11], s[6:7], 0, v[10:11]
	v_ashrrev_i32_e32 v13, 31, v0
	v_mov_b32_e32 v12, v0
	v_lshl_add_u64 v[10:11], v[12:13], 1, v[10:11]
	v_mov_b64_e32 v[12:13], 0x20000
	s_or_b64 exec, exec, s[12:13]
	v_ashrrev_i32_e32 v14, 8, v17
	v_lshlrev_b32_e32 v0, 2, v14
	v_and_b32_e32 v21, 3, v16
	v_xor_b32_e32 v0, v0, v16
	v_ashrrev_i32_e32 v15, 31, v14
	v_and_or_b32 v0, v0, 12, v21
	v_lshlrev_b64 v[14:15], 12, v[14:15]
	v_lshl_add_u64 v[14:15], s[6:7], 0, v[14:15]
	v_lshlrev_b32_e32 v0, 4, v0
	v_ashrrev_i32_e32 v20, 8, v5
	s_xor_b64 s[12:13], s[14:15], -1
	v_lshl_add_u64 v[14:15], v[14:15], 0, v[0:1]
	v_lshlrev_b32_e32 v0, 2, v20
	s_and_b64 s[14:15], s[14:15], exec
	v_xor_b32_e32 v0, v0, v16
	s_cselect_b32 s33, s22, s23
	v_and_or_b32 v0, v0, 12, v21
	v_ashrrev_i32_e32 v21, 31, v20
	s_add_i32 s41, s41, 0
	s_mov_b32 s14, m0
	s_mov_b32 m0, s41
	s_nop 0
	global_load_lds_dwordx4 v[2:3], off
	s_mov_b32 m0, s14
	v_lshlrev_b64 v[20:21], 12, v[20:21]
	s_add_i32 s42, s41, 0x2000
	s_mov_b32 s14, m0
	s_mov_b32 m0, s42
	s_nop 0
	global_load_lds_dwordx4 v[6:7], off
	s_mov_b32 m0, s14
	v_lshl_add_u64 v[20:21], s[6:7], 0, v[20:21]
	v_lshlrev_b32_e32 v0, 4, v0
	s_add_i32 s43, s41, 0x4000
	s_mov_b32 s14, m0
	s_mov_b32 m0, s43
	s_nop 0
	global_load_lds_dwordx4 v[10:11], off
	s_mov_b32 m0, s14
	v_lshrrev_b32_e32 v13, 5, v18
	v_lshl_add_u64 v[18:19], v[14:15], 0, s[36:37]
	v_lshl_add_u64 v[20:21], v[20:21], 0, v[0:1]
	s_add_i32 s44, s41, 0x6000
	s_mov_b32 s14, m0
	s_mov_b32 m0, s44
	s_nop 0
	global_load_lds_dwordx4 v[18:19], off
	s_mov_b32 m0, s14
	v_lshlrev_b32_e32 v170, 1, v4
	v_mov_b32_e32 v171, v1
	v_lshl_add_u64 v[22:23], v[20:21], 0, s[36:37]
	s_add_i32 s45, s41, 0x8000
	s_mov_b32 s14, m0
	s_mov_b32 m0, s45
	s_nop 0
	global_load_lds_dwordx4 v[22:23], off
	s_mov_b32 m0, s14
	v_lshl_add_u64 v[18:19], v[2:3], 0, v[170:171]
	v_lshlrev_b32_e32 v172, 1, v8
; DI unsigned cvt_pk_bf16(float lo, float hi) { unsigned r; asm volatile("v_cvt_pk_bf16_f32 %0, %1, %2" : "=v"(r) : "v"(lo), "v"(hi)); return r; }
; DI float bf_lo(unsigned w) { return __uint_as_float(w << 16); }
; DI float bf_hi(unsigned w) { return __uint_as_float(w & 0xffff0000u); }
; template <int DK>
; DI void attn_pass(const AttnSrc& s, const int q0, const float sc, LAS unsigned char* lds, f32x16 (&O)[4]) {
;     ...
;   auto issue = [&](int t, int buf) {
; #pragma unroll
;     for (int i = 0; i < KP; ++i) glds16(kp[i] + (size_t)t * kstr[i], (unsigned)__builtin_amdgcn_readfirstlane(lds0 + buf * STG + (wid + 8 * i) * 1024));
; #pragma unroll
;     for (int i = 0; i < 2; ++i) glds16(vp[i] + (size_t)t * vstr, (unsigned)__builtin_amdgcn_readfirstlane(lds0 + buf * STG + KSZ + (wid + 8 * i) * 1024));
;   };
; #pragma unroll
;   for (int i = 0; i < DPF; ++i) issue(i, i);
;   bf16x8 qf[NS];
; #pragma unroll
;   for (int i = 0; i < NS; ++i) qf[i] = *(const bf16x8*)(s.q + (size_t)(qw0 + r) * s.ldq + 16 * i + 8 * h);
; #pragma unroll
;   for (int i = 0; i < NS; ++i) asm volatile("" : "+v"(qf[i]));
;   constexpr bool REL = (DK == 64);
;   if (REL) {
; #pragma unroll
;   for (int i = 0; i < NS; ++i) {
;     const u32x4 w = __builtin_bit_cast(u32x4, qf[i]); u32x4 o;
;     o.x = cvt_pk_bf16(bf_lo(w.x) * sc, bf_hi(w.x) * sc); o.y = cvt_pk_bf16(bf_lo(w.y) * sc, bf_hi(w.y) * sc);
;     o.z = cvt_pk_bf16(bf_lo(w.z) * sc, bf_hi(w.z) * sc); o.w = cvt_pk_bf16(bf_lo(w.w) * sc, bf_hi(w.w) * sc);
;     qf[i] = __builtin_bit_cast(bf16x8, o);
;   }
;   }
;   f32x16 negm;
; #pragma unroll
;   for (int j = 0; j < 16; ++j) negm[j] = 0.f;
;   if (REL) asm volatile("" : "+v"(negm));
;   const int kx = (DK == 64) ? (r & 7) : ((r >> 1) & 7);
;   const int krow = r * ROWB;
;   const int i15 = lane & 15;
;   const int vrow = (4 * h + (i15 >> 2)) * 256 + ((lane >> 4) & 1) * 32 + (lane & 3) * 8;
;   const int vx = (i15 >> 2) & 3;
;   int buf = 0, pbuf = DPF;
	v_mov_b32_e32 v173, v1
	s_add_i32 s14, s41, 0xa000
	s_mov_b32 s15, m0
	s_mov_b32 m0, s14
	s_nop 0
	global_load_lds_dwordx4 v[18:19], off
	s_mov_b32 m0, s15
	v_lshl_add_u64 v[18:19], v[6:7], 0, v[172:173]
	v_lshlrev_b32_e32 v174, 1, v12
	v_mov_b32_e32 v175, v1
	s_add_i32 s14, s41, 0xc000
	s_mov_b32 s15, m0
	s_mov_b32 m0, s14
	s_nop 0
	global_load_lds_dwordx4 v[18:19], off
	s_mov_b32 m0, s15
	v_lshl_add_u64 v[18:19], v[10:11], 0, v[174:175]
	s_lshl_b32 s40, s40, 5
	s_add_i32 s14, s41, 0xe000
	s_mov_b32 s15, m0
	s_mov_b32 m0, s14
	s_nop 0
	global_load_lds_dwordx4 v[18:19], off
	s_mov_b32 m0, s15
	v_lshl_add_u64 v[18:19], v[14:15], 0, s[90:91]
	v_and_b32_e32 v9, 31, v16
	s_add_i32 s40, s40, s33
	s_add_i32 s14, s41, 0x10000
	s_mov_b32 s15, m0
	s_mov_b32 m0, s14
	s_nop 0
	global_load_lds_dwordx4 v[18:19], off
	s_mov_b32 m0, s15
	v_lshl_add_u64 v[18:19], v[20:21], 0, s[90:91]
	s_add_i32 s14, s41, 0x12000
	s_mov_b32 s15, m0
	s_mov_b32 m0, s14
	s_nop 0
	global_load_lds_dwordx4 v[18:19], off
	s_mov_b32 m0, s15
	v_or_b32_e32 v167, s40, v9
	v_mov_b64_e32 v[18:19], s[4:5]
	v_mad_i64_i32 v[18:19], s[14:15], v167, s88, v[18:19]
	v_lshlrev_b32_e32 v0, 4, v13
	v_lshl_add_u64 v[18:19], v[18:19], 0, v[0:1]
	global_load_dwordx4 v[98:101], v[18:19], off
	global_load_dwordx4 v[102:105], v[18:19], off offset:32
	global_load_dwordx4 v[106:109], v[18:19], off offset:64
	global_load_dwordx4 v[110:113], v[18:19], off offset:96
	global_load_dwordx4 v[114:117], v[18:19], off offset:128
	global_load_dwordx4 v[118:121], v[18:19], off offset:160
	global_load_dwordx4 v[122:125], v[18:19], off offset:192
	global_load_dwordx4 v[126:129], v[18:19], off offset:224
	global_load_dwordx4 v[130:133], v[18:19], off offset:256
	global_load_dwordx4 v[134:137], v[18:19], off offset:288
	global_load_dwordx4 v[138:141], v[18:19], off offset:320
	global_load_dwordx4 v[142:145], v[18:19], off offset:352
	v_lshrrev_b32_e32 v0, 1, v16
	v_bfe_u32 v5, v16, 1, 3
	v_bitop3_b32 v0, v13, v0, 7 bitop3:0x78
	v_lshlrev_b32_e32 v209, 4, v0
	v_bitop3_b32 v0, v13, v5, 2 bitop3:0x36
	v_lshlrev_b32_e32 v210, 4, v0
	v_bitop3_b32 v0, v13, v5, 4 bitop3:0x36
	v_lshlrev_b32_e32 v213, 4, v0
	v_bitop3_b32 v0, v13, v5, 6 bitop3:0x36
	v_lshlrev_b32_e32 v214, 4, v0
	v_lshlrev_b32_e32 v0, 2, v12
	v_lshl_add_u64 v[180:181], v[10:11], 0, v[0:1]
	v_lshlrev_b32_e32 v0, 2, v8
	v_mul_u32_u24_e32 v204, 0x180, v9
	v_bfe_u32 v9, v16, 2, 2
	v_lshl_add_u64 v[178:179], v[14:15], 0, s[92:93]
	v_lshl_add_u64 v[182:183], v[6:7], 0, v[0:1]
	v_lshlrev_b32_e32 v0, 2, v4
	v_mov_b32_e32 v14, v1
	v_mov_b32_e32 v15, v1
	s_add_i32 s14, s33, 0x100
	v_lshlrev_b32_e32 v205, 10, v13
	v_lshlrev_b32_e32 v206, 8, v9
	v_lshlrev_b32_e32 v17, 1, v16
	v_lshlrev_b32_e32 v16, 3, v16
	v_lshlrev_b32_e32 v211, 6, v9
	v_lshlrev_b32_e32 v212, 2, v13
	v_lshl_add_u64 v[176:177], v[20:21], 0, s[92:93]
	v_lshl_add_u64 v[184:185], v[2:3], 0, v[0:1]
	v_mov_b32_e32 v0, v1
	v_mov_b32_e32 v2, v1
	v_mov_b32_e32 v3, v1
	v_mov_b32_e32 v4, v1
	v_mov_b32_e32 v5, v1
	v_mov_b32_e32 v6, v1
	v_mov_b32_e32 v7, v1
	v_mov_b32_e32 v8, v1
	v_mov_b32_e32 v9, v1
	v_mov_b32_e32 v10, v1
	v_mov_b32_e32 v11, v1
	v_mov_b32_e32 v12, v1
	v_mov_b32_e32 v13, v1
	v_mov_b64_e32 v[64:65], v[14:15]
	v_mov_b64_e32 v[48:49], v[14:15]
	v_mov_b64_e32 v[32:33], v[14:15]
	s_lshr_b32 s47, s14, 6
	v_and_b32_e32 v207, 32, v17
	v_and_b32_e32 v208, 24, v16
	v_mov_b64_e32 v[62:63], v[12:13]
	v_mov_b64_e32 v[60:61], v[10:11]
	v_mov_b64_e32 v[58:59], v[8:9]
	v_mov_b64_e32 v[56:57], v[6:7]
	v_mov_b64_e32 v[54:55], v[4:5]
	v_mov_b64_e32 v[52:53], v[2:3]
	v_mov_b64_e32 v[50:51], v[0:1]
	v_mov_b64_e32 v[46:47], v[12:13]
	v_mov_b64_e32 v[44:45], v[10:11]
	v_mov_b64_e32 v[42:43], v[8:9]
	v_mov_b64_e32 v[40:41], v[6:7]
	v_mov_b64_e32 v[38:39], v[4:5]
	v_mov_b64_e32 v[36:37], v[2:3]
	v_mov_b64_e32 v[34:35], v[0:1]
	v_mov_b64_e32 v[30:31], v[12:13]
	v_mov_b64_e32 v[28:29], v[10:11]
	v_mov_b64_e32 v[26:27], v[8:9]
	v_mov_b64_e32 v[24:25], v[6:7]
	v_mov_b64_e32 v[22:23], v[4:5]
	v_mov_b64_e32 v[20:21], v[2:3]
	v_mov_b64_e32 v[18:19], v[0:1]
	v_mov_b64_e32 v[16:17], v[14:15]
	s_mov_b32 s46, 2
	s_add_i32 s52, s47, -1
	s_or_b32 s53, s40, 31
	v_xor_b32_e32 v215, 64, v211
	v_xor_b32_e32 v216, 0x80, v211
	v_xor_b32_e32 v217, 0xc0, v211
	s_mov_b32 s54, 0
	v_mov_b32_e32 v218, 0
	v_mov_b32_e32 v219, 0xff800000
	s_mov_b32 s55, 63
	v_mov_b64_e32 v[14:15], v[12:13]
	v_mov_b64_e32 v[12:13], v[10:11]
	v_mov_b64_e32 v[10:11], v[8:9]
	v_mov_b64_e32 v[8:9], v[6:7]
	v_mov_b64_e32 v[6:7], v[4:5]
	v_mov_b64_e32 v[4:5], v[2:3]
	v_mov_b64_e32 v[2:3], v[0:1]
	s_mov_b32 s56, 0
	s_waitcnt vmcnt(11)
	s_waitcnt vmcnt(10)
	s_waitcnt vmcnt(9)
	s_waitcnt vmcnt(8)
	s_waitcnt vmcnt(7)
	s_waitcnt vmcnt(6)
	s_waitcnt vmcnt(5)
	s_waitcnt vmcnt(4)
	s_waitcnt vmcnt(3)
	s_waitcnt vmcnt(2)
	s_waitcnt vmcnt(1)
	s_waitcnt vmcnt(0)
	s_branch .LBB0_138
